# nt hint on read-once prep-phase input loads (x rows, cache_diff_k, cache_diff_v) so prep outputs stay cache resident
# speedup vs baseline: 1.1431x; 1.0060x over previous
; __device__ __forceinline__ unsigned pk2(float lo, float hi) { f32v2_t v = {lo, hi}; bf16v2_t r = __builtin_convertvector(v, bf16v2_t); return __builtin_bit_cast(unsigned, r); }
; __device__ void phase_prep(const Params& p) {
;     ...
;     for (int t = gw; t < T; t += nw) {
;       const float* x = (t < TP) ? p.in[0] + (size_t)t * DM : p.in[1] + (size_t)(t - TP) * DM;
;       f32x4 v[4]; float ss = 0.f;
; #pragma unroll
;       for (int i = 0; i < 4; ++i) { v[i] = *(const f32x4*)(x + i * 256 + lane * 4); ss += v[i][0] * v[i][0] + v[i][1] * v[i][1] + v[i][2] * v[i][2] + v[i][3] * v[i][3]; }
;       ss = wave_sum(ss);
;       const float rs = rsqrtf(ss * (1.f / DM) + EPS);
; #pragma unroll
;       for (int i = 0; i < 4; ++i) {
;         f32x4 gg = *(const f32x4*)(g + i * 256 + lane * 4);
;         u32x2 w; w.x = pk2(v[i][0] * rs * gg[0], v[i][1] * rs * gg[1]); w.y = pk2(v[i][2] * rs * gg[2], v[i][3] * rs * gg[3]);
;         *(u32x2*)(hb + (size_t)t * LDH + i * 256 + lane * 4) = w;
;       }
.LBB0_69:
	s_or_b64 exec, exec, s[2:3]
	v_mov_b32_e32 v35, v17
	v_lshl_add_u64 v[4:5], v[0:1], 0, v[34:35]
	global_load_dwordx4 v[8:11], v[4:5], off nt
	s_waitcnt lgkmcnt(0)
	global_load_dwordx4 v[0:3], v[4:5], off offset:1024 nt
	global_load_dwordx4 v[12:15], v[4:5], off offset:2048 nt
	global_load_dwordx4 v[4:7], v[4:5], off offset:3072 nt
	s_mov_b32 s2, 0x800000
	v_lshl_add_u64 v[42:43], v[42:43], 0, s[56:57]
	v_lshl_add_u64 v[40:41], v[40:41], 0, s[42:43]
	s_waitcnt vmcnt(3)
	v_mov_b32_e32 v74, v9
	s_waitcnt vmcnt(2)
	v_mov_b32_e32 v75, v1
	v_mov_b32_e32 v76, v8
	v_mov_b32_e32 v77, v0
	v_pk_mul_f32 v[74:75], v[74:75], v[74:75]
	s_nop 0
	v_pk_fma_f32 v[76:77], v[76:77], v[76:77], v[74:75]
	v_mov_b32_e32 v74, v10
	v_mov_b32_e32 v75, v2
	v_pk_fma_f32 v[76:77], v[74:75], v[74:75], v[76:77]
	v_mov_b32_e32 v74, v11
	v_mov_b32_e32 v75, v3
	v_pk_fma_f32 v[44:45], v[74:75], v[74:75], v[76:77]
	s_nop 0
	v_add_f32_e32 v16, v44, v45
	s_waitcnt vmcnt(1)
	v_mov_b32_e32 v72, v13
	s_waitcnt vmcnt(0)
	v_mov_b32_e32 v73, v5
	v_mov_b32_e32 v70, v12
	v_mov_b32_e32 v71, v4
	v_pk_mul_f32 v[72:73], v[72:73], v[72:73]
	s_nop 0
	v_pk_fma_f32 v[70:71], v[70:71], v[70:71], v[72:73]
	v_mov_b32_e32 v72, v14
	v_mov_b32_e32 v73, v6
	v_pk_fma_f32 v[70:71], v[72:73], v[72:73], v[70:71]
	v_mov_b32_e32 v72, v15
	v_mov_b32_e32 v73, v7
	v_pk_fma_f32 v[70:71], v[72:73], v[72:73], v[70:71]
	s_nop 0
	v_add_f32_e32 v16, v16, v70
	v_add_f32_e32 v16, v16, v71
	ds_bpermute_b32 v35, v37, v16
	s_waitcnt lgkmcnt(0)
	v_add_f32_e32 v16, v16, v35
	ds_bpermute_b32 v35, v39, v16
	s_waitcnt lgkmcnt(0)
	v_add_f32_e32 v16, v16, v35
	ds_bpermute_b32 v35, v66, v16
	s_waitcnt lgkmcnt(0)
	v_add_f32_e32 v16, v16, v35
	ds_bpermute_b32 v35, v67, v16
	s_waitcnt lgkmcnt(0)
	v_add_f32_e32 v16, v16, v35
	ds_bpermute_b32 v35, v68, v16
	s_waitcnt lgkmcnt(0)
	v_add_f32_e32 v16, v16, v35
	ds_bpermute_b32 v35, v69, v16
	s_waitcnt lgkmcnt(0)
	v_add_f32_e32 v16, v16, v35
	v_fmamk_f32 v16, v16, 0x3a800000, v55
	v_cmp_gt_f32_e32 vcc, s2, v16
	v_mul_f32_e32 v35, 0x4b800000, v16
	v_mad_u64_u32 v[44:45], s[2:3], v46, s34, v[18:19]
	v_cndmask_b32_e32 v16, v16, v35, vcc
	v_rsq_f32_e32 v16, v16
	v_mov_b32_e32 v46, v45
	v_mad_u64_u32 v[46:47], s[2:3], v47, s34, v[46:47]
	v_mul_f32_e32 v35, 0x45800000, v16
	v_cndmask_b32_e32 v16, v16, v35, vcc
	v_pk_mul_f32 v[8:9], v[8:9], v[16:17] op_sel_hi:[1,0]
	v_pk_mul_f32 v[10:11], v[10:11], v[16:17] op_sel_hi:[1,0]
	v_mov_b32_e32 v45, v46
	v_pk_mul_f32 v[0:1], v[0:1], v[16:17] op_sel_hi:[1,0]
	v_pk_mul_f32 v[2:3], v[2:3], v[16:17] op_sel_hi:[1,0]
	v_pk_mul_f32 v[4:5], v[4:5], v[16:17] op_sel_hi:[1,0]
	s_mov_b32 s2, 0x81ff
	v_cmp_lt_i32_e32 vcc, s2, v42
	s_or_b64 s[0:1], vcc, s[0:1]
	v_pk_mul_f32 v[12:13], v[12:13], v[16:17] op_sel_hi:[1,0]
	v_pk_mul_f32 v[14:15], v[14:15], v[16:17] op_sel_hi:[1,0]
	v_pk_mul_f32 v[6:7], v[6:7], v[16:17] op_sel_hi:[1,0]
	v_pk_mul_f32 v[8:9], v[100:101], v[8:9]
	v_pk_mul_f32 v[10:11], v[102:103], v[10:11]
	v_pk_mul_f32 v[0:1], v[104:105], v[0:1]
	v_pk_mul_f32 v[2:3], v[106:107], v[2:3]
	v_cvt_pk_bf16_f32 v8, v8, v9
	v_cvt_pk_bf16_f32 v9, v10, v11
	global_store_dwordx2 v[44:45], v[8:9], off
	v_pk_mul_f32 v[12:13], v[108:109], v[12:13]
	v_pk_mul_f32 v[14:15], v[110:111], v[14:15]
	v_cvt_pk_bf16_f32 v0, v0, v1
	v_cvt_pk_bf16_f32 v1, v2, v3
	global_store_dwordx2 v[44:45], v[0:1], off offset:512
	v_pk_mul_f32 v[4:5], v[112:113], v[4:5]
	v_pk_mul_f32 v[6:7], v[114:115], v[6:7]
	v_cvt_pk_bf16_f32 v12, v12, v13
	v_cvt_pk_bf16_f32 v13, v14, v15
	global_store_dwordx2 v[44:45], v[12:13], off offset:1024
	v_cvt_pk_bf16_f32 v4, v4, v5
	v_cvt_pk_bf16_f32 v5, v6, v7
	global_store_dwordx2 v[44:45], v[4:5], off offset:1536
	s_andn2_b64 exec, exec, s[0:1]
	s_cbranch_execz .LBB0_72

; __device__ __forceinline__ unsigned pk2(float lo, float hi) { f32v2_t v = {lo, hi}; bf16v2_t r = __builtin_convertvector(v, bf16v2_t); return __builtin_bit_cast(unsigned, r); }
; __device__ void phase_prep(const Params& p) {
;     ...
;     bf16_t* dk = (bf16_t*)(ws + W_D); const float* src = p.in[2];
;     for (int u = gtid; u < 8 * PAST * 256; u += gthreads) {
;       const int e = u * 4; const int row = e >> 10, c = e & 1023; const int b = row >> 11, j = row & 2047;
;       f32x4 v = *(const f32x4*)(src + (size_t)e);
;       u32x2 w; w.x = pk2(v[0], v[1]); w.y = pk2(v[2], v[3]);
;       *(u32x2*)(dk + (size_t)(TP + b * LKS + j) * LDH + c) = w;
;     }
.LBB0_74:
	s_waitcnt lgkmcnt(0)
	s_mov_b32 s54, 0x3fffff
	s_mov_b64 s[74:75], exec
	v_mov_b32_e32 v112, v2
	v_lshlrev_b32_e32 v120, 2, v0
	global_load_dwordx4 v[80:83], v120, s[68:69] nt
	v_add_u32_e32 v113, s60, v112
	v_lshl_add_u32 v121, s24, 2, v120
	v_cmp_ge_i32_e32 vcc, s54, v113
	s_and_b64 exec, exec, vcc
	global_load_dwordx4 v[84:87], v121, s[68:69] nt
	v_add_u32_e32 v114, s60, v113
	v_lshl_add_u32 v122, s24, 2, v121
	v_cmp_ge_i32_e32 vcc, s54, v114
	s_and_b64 exec, exec, vcc
	global_load_dwordx4 v[88:91], v122, s[68:69] nt
	v_add_u32_e32 v115, s60, v114
	v_lshl_add_u32 v123, s24, 2, v122
	v_cmp_ge_i32_e32 vcc, s54, v115
	s_and_b64 exec, exec, vcc
	global_load_dwordx4 v[92:95], v123, s[68:69] nt
	v_add_u32_e32 v116, s60, v115
	v_lshl_add_u32 v124, s24, 2, v123
	v_cmp_ge_i32_e32 vcc, s54, v116
	s_and_b64 exec, exec, vcc
	global_load_dwordx4 v[96:99], v124, s[68:69] nt
	v_add_u32_e32 v117, s60, v116
	v_lshl_add_u32 v125, s24, 2, v124
	v_cmp_ge_i32_e32 vcc, s54, v117
	s_and_b64 exec, exec, vcc
	global_load_dwordx4 v[100:103], v125, s[68:69] nt
	v_add_u32_e32 v118, s60, v117
	v_lshl_add_u32 v126, s24, 2, v125
	v_cmp_ge_i32_e32 vcc, s54, v118
	s_and_b64 exec, exec, vcc
	global_load_dwordx4 v[104:107], v126, s[68:69] nt
	v_add_u32_e32 v119, s60, v118
	v_lshl_add_u32 v127, s24, 2, v126
	v_cmp_ge_i32_e32 vcc, s54, v119
	s_and_b64 exec, exec, vcc
	global_load_dwordx4 v[108:111], v127, s[68:69] nt
	s_mov_b64 exec, s[74:75]
	v_ashrrev_i32_e32 v74, 19, v112
	v_bfe_u32 v75, v112, 8, 11
	v_mul_i32_i24_e32 v74, 0x840, v74
	v_add3_u32 v74, v74, v75, s6
	v_mul_lo_u32 v74, v74, s34
	v_and_b32_e32 v75, 0xff0, v120
	v_lshrrev_b32_e32 v75, 1, v75
	v_add_u32_e32 v74, v74, v75
	s_waitcnt vmcnt(7)
	v_cvt_pk_bf16_f32 v80, v80, v81
	v_cvt_pk_bf16_f32 v81, v82, v83
	global_store_dwordx2 v74, v[80:81], s[44:45]
	s_mov_b64 exec, s[74:75]
	v_cmp_ge_i32_e32 vcc, s54, v113
	s_and_b64 exec, exec, vcc
	v_ashrrev_i32_e32 v74, 19, v113
	v_bfe_u32 v75, v113, 8, 11
	v_mul_i32_i24_e32 v74, 0x840, v74
	v_add3_u32 v74, v74, v75, s6
	v_mul_lo_u32 v74, v74, s34
	v_and_b32_e32 v75, 0xff0, v121
	v_lshrrev_b32_e32 v75, 1, v75
	v_add_u32_e32 v74, v74, v75
	s_waitcnt vmcnt(7)
	v_cvt_pk_bf16_f32 v84, v84, v85
	v_cvt_pk_bf16_f32 v85, v86, v87
	global_store_dwordx2 v74, v[84:85], s[44:45]
	s_mov_b64 exec, s[74:75]
	v_cmp_ge_i32_e32 vcc, s54, v114
	s_and_b64 exec, exec, vcc
	v_ashrrev_i32_e32 v74, 19, v114
	v_bfe_u32 v75, v114, 8, 11
	v_mul_i32_i24_e32 v74, 0x840, v74
	v_add3_u32 v74, v74, v75, s6
	v_mul_lo_u32 v74, v74, s34
	v_and_b32_e32 v75, 0xff0, v122
	v_lshrrev_b32_e32 v75, 1, v75
	v_add_u32_e32 v74, v74, v75
	s_waitcnt vmcnt(7)
	v_cvt_pk_bf16_f32 v88, v88, v89
	v_cvt_pk_bf16_f32 v89, v90, v91
	global_store_dwordx2 v74, v[88:89], s[44:45]
	s_mov_b64 exec, s[74:75]
	v_cmp_ge_i32_e32 vcc, s54, v115
	s_and_b64 exec, exec, vcc
	v_ashrrev_i32_e32 v74, 19, v115
	v_bfe_u32 v75, v115, 8, 11
	v_mul_i32_i24_e32 v74, 0x840, v74
	v_add3_u32 v74, v74, v75, s6
	v_mul_lo_u32 v74, v74, s34
	v_and_b32_e32 v75, 0xff0, v123
	v_lshrrev_b32_e32 v75, 1, v75
	v_add_u32_e32 v74, v74, v75
	s_waitcnt vmcnt(7)
	v_cvt_pk_bf16_f32 v92, v92, v93
	v_cvt_pk_bf16_f32 v93, v94, v95
	global_store_dwordx2 v74, v[92:93], s[44:45]
	s_mov_b64 exec, s[74:75]
	v_cmp_ge_i32_e32 vcc, s54, v116
	s_and_b64 exec, exec, vcc
	v_ashrrev_i32_e32 v74, 19, v116
	v_bfe_u32 v75, v116, 8, 11
	v_mul_i32_i24_e32 v74, 0x840, v74
	v_add3_u32 v74, v74, v75, s6
	v_mul_lo_u32 v74, v74, s34
	v_and_b32_e32 v75, 0xff0, v124
	v_lshrrev_b32_e32 v75, 1, v75
	v_add_u32_e32 v74, v74, v75
	s_waitcnt vmcnt(7)
	v_cvt_pk_bf16_f32 v96, v96, v97
	v_cvt_pk_bf16_f32 v97, v98, v99
	global_store_dwordx2 v74, v[96:97], s[44:45]
	s_mov_b64 exec, s[74:75]
	v_cmp_ge_i32_e32 vcc, s54, v117
	s_and_b64 exec, exec, vcc
	v_ashrrev_i32_e32 v74, 19, v117
	v_bfe_u32 v75, v117, 8, 11
	v_mul_i32_i24_e32 v74, 0x840, v74
	v_add3_u32 v74, v74, v75, s6
	v_mul_lo_u32 v74, v74, s34
	v_and_b32_e32 v75, 0xff0, v125
	v_lshrrev_b32_e32 v75, 1, v75
	v_add_u32_e32 v74, v74, v75
	s_waitcnt vmcnt(7)
	v_cvt_pk_bf16_f32 v100, v100, v101
	v_cvt_pk_bf16_f32 v101, v102, v103
	global_store_dwordx2 v74, v[100:101], s[44:45]
	s_mov_b64 exec, s[74:75]
	v_cmp_ge_i32_e32 vcc, s54, v118
	s_and_b64 exec, exec, vcc
	v_ashrrev_i32_e32 v74, 19, v118
	v_bfe_u32 v75, v118, 8, 11
	v_mul_i32_i24_e32 v74, 0x840, v74
	v_add3_u32 v74, v74, v75, s6
	v_mul_lo_u32 v74, v74, s34
	v_and_b32_e32 v75, 0xff0, v126
	v_lshrrev_b32_e32 v75, 1, v75
	v_add_u32_e32 v74, v74, v75
	s_waitcnt vmcnt(7)
	v_cvt_pk_bf16_f32 v104, v104, v105
	v_cvt_pk_bf16_f32 v105, v106, v107
	global_store_dwordx2 v74, v[104:105], s[44:45]
	s_mov_b64 exec, s[74:75]
	v_cmp_ge_i32_e32 vcc, s54, v119
	s_and_b64 exec, exec, vcc
	v_ashrrev_i32_e32 v74, 19, v119
	v_bfe_u32 v75, v119, 8, 11
	v_mul_i32_i24_e32 v74, 0x840, v74
	v_add3_u32 v74, v74, v75, s6
	v_mul_lo_u32 v74, v74, s34
	v_and_b32_e32 v75, 0xff0, v127
	v_lshrrev_b32_e32 v75, 1, v75
	v_add_u32_e32 v74, v74, v75
	s_waitcnt vmcnt(7)
	v_cvt_pk_bf16_f32 v108, v108, v109
	v_cvt_pk_bf16_f32 v109, v110, v111
	global_store_dwordx2 v74, v[108:109], s[44:45]
	s_mov_b64 exec, s[74:75]
	v_add_u32_e32 v2, s60, v119
	v_lshl_add_u32 v0, s24, 2, v127
	v_lshrrev_b32_e32 v0, 2, v0
	v_cmp_ge_i32_e32 vcc, s54, v2
	s_and_b64 exec, exec, vcc
	s_cbranch_execnz .LBB0_74

; __device__ __forceinline__ unsigned pk2(float lo, float hi) { f32v2_t v = {lo, hi}; bf16v2_t r = __builtin_convertvector(v, bf16v2_t); return __builtin_bit_cast(unsigned, r); }
; __device__ __forceinline__ int kperm(int k) { return (k & ~12) | ((k & 4) << 1) | ((k & 8) >> 1); }
; __device__ void phase_prep(const Params& p) {
;     ...
;     for (int u = gtid; u < 8 * 256 * 1024; u += gthreads) {
;       const int c = u & 1023, pg = (u >> 10) & 255, b = u >> 18;
;       const int p0 = pg * 8;
;       float v[8];
; #pragma unroll
;       for (int i = 0; i < 8; ++i) { const int key = kperm(p0 + i); v[i] = src[((size_t)(b * PAST + key)) * 1024 + c]; }
;       u32x4 w; w.x = pk2(v[0], v[1]); w.y = pk2(v[2], v[3]); w.z = pk2(v[4], v[5]); w.w = pk2(v[6], v[7]);
;       *(u32x4*)(vt + ((size_t)(b * 1024 + c)) * LKS + p0) = w;
;     }
.LBB0_83:
	v_ashrrev_i32_e32 v8, 18, v0
	v_lshrrev_b32_e32 v4, 7, v0
	v_lshrrev_b32_e32 v2, 8, v0
	v_and_b32_e32 v5, 4, v2
	v_lshlrev_b32_e32 v6, 11, v8
	v_and_b32_e32 v4, 0x7f0, v4
	s_waitcnt lgkmcnt(1)
	v_and_b32_e32 v1, 0x3ff, v0
	v_or3_b32 v4, v6, v5, v4
	v_lshlrev_b32_e32 v16, 2, v1
	v_ashrrev_i32_e32 v5, 31, v4
	s_waitcnt lgkmcnt(0)
	v_lshl_add_u64 v[2:3], s[70:71], 0, v[16:17]
	v_lshlrev_b64 v[6:7], 12, v[4:5]
	v_lshl_add_u64 v[6:7], v[2:3], 0, v[6:7]
	global_load_dword v9, v[6:7], off nt
	v_or_b32_e32 v6, 1, v4
	v_ashrrev_i32_e32 v7, 31, v6
	v_lshlrev_b64 v[6:7], 12, v[6:7]
	v_lshl_add_u64 v[6:7], v[2:3], 0, v[6:7]
	global_load_dword v10, v[6:7], off nt
	v_or_b32_e32 v6, 2, v4
	v_ashrrev_i32_e32 v7, 31, v6
	v_lshlrev_b64 v[6:7], 12, v[6:7]
	v_lshl_add_u64 v[6:7], v[2:3], 0, v[6:7]
	global_load_dword v11, v[6:7], off nt
	v_or_b32_e32 v6, 3, v4
	v_ashrrev_i32_e32 v7, 31, v6
	v_lshlrev_b64 v[6:7], 12, v[6:7]
	v_lshl_add_u64 v[6:7], v[2:3], 0, v[6:7]
	global_load_dword v12, v[6:7], off nt
	v_or_b32_e32 v6, 8, v4
	v_ashrrev_i32_e32 v7, 31, v6
	v_lshlrev_b64 v[6:7], 12, v[6:7]
	v_lshl_add_u64 v[6:7], v[2:3], 0, v[6:7]
	global_load_dword v13, v[6:7], off nt
	v_or_b32_e32 v6, 9, v4
	v_ashrrev_i32_e32 v7, 31, v6
	v_lshlrev_b64 v[6:7], 12, v[6:7]
	v_lshl_add_u64 v[6:7], v[2:3], 0, v[6:7]
	global_load_dword v14, v[6:7], off nt
	v_or_b32_e32 v6, 10, v4
	v_or_b32_e32 v4, 11, v4
	v_ashrrev_i32_e32 v7, 31, v6
	v_ashrrev_i32_e32 v5, 31, v4
	v_lshlrev_b64 v[6:7], 12, v[6:7]
	v_lshlrev_b64 v[4:5], 12, v[4:5]
	v_lshl_add_u64 v[6:7], v[2:3], 0, v[6:7]
	v_lshl_add_u64 v[2:3], v[2:3], 0, v[4:5]
	global_load_dword v6, v[6:7], off nt
	v_lshl_or_b32 v1, v8, 10, v1
	global_load_dword v5, v[2:3], off nt
	v_mul_hi_i32_i24_e32 v7, 0x1080, v1
	s_mov_b32 s54, 0x1fffff
	s_waitcnt vmcnt(6)
	v_cvt_pk_bf16_f32 v2, v9, v10
	s_waitcnt vmcnt(4)
	v_cvt_pk_bf16_f32 v3, v11, v12
	s_waitcnt vmcnt(2)
	v_cvt_pk_bf16_f32 v4, v13, v14
	s_waitcnt vmcnt(0)
	v_cvt_pk_bf16_f32 v5, v6, v5
	v_mul_i32_i24_e32 v6, 0x1080, v1
	v_lshrrev_b32_e32 v1, 6, v0
	v_add_u32_e32 v0, s60, v0
	v_lshl_add_u64 v[6:7], s[50:51], 0, v[6:7]
	v_and_b32_e32 v16, 0xff0, v1
	v_cmp_lt_i32_e32 vcc, s54, v0
	v_lshl_add_u64 v[6:7], v[6:7], 0, v[16:17]
	s_or_b64 s[2:3], vcc, s[2:3]
	global_store_dwordx4 v[6:7], v[2:5], off
	s_andn2_b64 exec, exec, s[2:3]
	s_cbranch_execnz .LBB0_83
